# S5-out GEMM compute segments rewritten: in-place accumulators, eight fragment reads of a k-step in flight together
# baseline (speedup 1.0000x reference)
; #define GLOAD(RA, RB, kt) { const int k_ = (kt) * 64 + lc * 8; const long ko_ = (long)(k_ >> a.segshift) * a.segstride + (k_ & segmask); \
;     _Pragma("unroll") for (int i = 0; i < 4; ++i) RA[i] = *(const u32x4*)(ap[i] + ko_); \
;     _Pragma("unroll") for (int i = 0; i < NBL; ++i) RB[i] = *(const u32x4*)(bp + (long)(32 * i) * ldb + (kt) * 64); }
; #define LSTORE(RA, RB, buf) { char* s_ = smem + (buf) * STAGE; \
;     _Pragma("unroll") for (int i = 0; i < 4; ++i) *(u32x4*)(s_ + wofs + i * 4096) = RA[i]; \
;     _Pragma("unroll") for (int i = 0; i < NBL; ++i) *(u32x4*)(s_ + ABYTES + wofs + i * 4096) = RB[i]; }
; #define BAR() { asm volatile("s_waitcnt lgkmcnt(0)" ::: "memory"); __builtin_amdgcn_s_barrier(); asm volatile("" ::: "memory"); }
; template <int WN, bool SWAP>
; DEV void gemm_core(f32x4 (&acc)[4][WN], const ASrc& a, const bf16_t* __restrict__ Bt, long ldb, int K, char* smem) {
;     ...
;   __builtin_amdgcn_sched_barrier(0);
;   GLOAD(ra0, rb0, 0); GLOAD(ra1, rb1, 1); LSTORE(ra0, rb0, 0); BAR();
; #pragma nounroll
;   for (int kt = 0; kt < nk; kt += 2) {
;     if (kt + 2 < nk) GLOAD(ra0, rb0, kt + 2);
;     COMPUTE(0);
;     LSTORE(ra1, rb1, 1);
.LBB0_123:
	v_add_u32_e32 v151, v147, v149
	v_add_u32_e32 v153, v148, v149
	v_add_u32_e32 v152, v147, v150
	v_add_u32_e32 v199, v148, v150
	ds_read_b128 v[170:173], v153 offset:16384
	ds_read_b128 v[174:177], v153 offset:18432
	ds_read_b128 v[178:181], v153 offset:20480
	ds_read_b128 v[182:185], v153 offset:22528
	ds_read_b128 v[154:157], v151 offset:0
	ds_read_b128 v[158:161], v151 offset:2048
	ds_read_b128 v[162:165], v151 offset:4096
	ds_read_b128 v[166:169], v151 offset:6144
	s_waitcnt lgkmcnt(3)
	v_mfma_f32_16x16x32_bf16 v[64:67], v[170:173], v[154:157], v[64:67]
	v_mfma_f32_16x16x32_bf16 v[60:63], v[174:177], v[154:157], v[60:63]
	v_mfma_f32_16x16x32_bf16 v[56:59], v[178:181], v[154:157], v[56:59]
	v_mfma_f32_16x16x32_bf16 v[52:55], v[182:185], v[154:157], v[52:55]
	ds_read_b128 v[186:189], v199 offset:16384
	s_waitcnt lgkmcnt(3)
	v_mfma_f32_16x16x32_bf16 v[48:51], v[170:173], v[158:161], v[48:51]
	v_mfma_f32_16x16x32_bf16 v[44:47], v[174:177], v[158:161], v[44:47]
	v_mfma_f32_16x16x32_bf16 v[36:39], v[178:181], v[158:161], v[36:39]
	v_mfma_f32_16x16x32_bf16 v[32:35], v[182:185], v[158:161], v[32:35]
	ds_read_b128 v[190:193], v199 offset:18432
	s_waitcnt lgkmcnt(3)
	v_mfma_f32_16x16x32_bf16 v[28:31], v[170:173], v[162:165], v[28:31]
	v_mfma_f32_16x16x32_bf16 v[24:27], v[174:177], v[162:165], v[24:27]
	v_mfma_f32_16x16x32_bf16 v[20:23], v[178:181], v[162:165], v[20:23]
	v_mfma_f32_16x16x32_bf16 v[16:19], v[182:185], v[162:165], v[16:19]
	ds_read_b128 v[194:197], v199 offset:20480
	s_waitcnt lgkmcnt(3)
	v_mfma_f32_16x16x32_bf16 v[12:15], v[170:173], v[166:169], v[12:15]
	v_mfma_f32_16x16x32_bf16 v[8:11], v[174:177], v[166:169], v[8:11]
	v_mfma_f32_16x16x32_bf16 v[4:7], v[178:181], v[166:169], v[4:7]
	v_mfma_f32_16x16x32_bf16 v[0:3], v[182:185], v[166:169], v[0:3]
	ds_read_b128 v[182:185], v199 offset:22528
	ds_read_b128 v[154:157], v152 offset:0
	ds_read_b128 v[158:161], v152 offset:2048
	ds_read_b128 v[162:165], v152 offset:4096
	ds_read_b128 v[166:169], v152 offset:6144
	s_waitcnt lgkmcnt(3)
	v_mfma_f32_16x16x32_bf16 v[64:67], v[186:189], v[154:157], v[64:67]
	v_mfma_f32_16x16x32_bf16 v[60:63], v[190:193], v[154:157], v[60:63]
	v_mfma_f32_16x16x32_bf16 v[56:59], v[194:197], v[154:157], v[56:59]
	v_mfma_f32_16x16x32_bf16 v[52:55], v[182:185], v[154:157], v[52:55]
	s_waitcnt lgkmcnt(2)
	v_mfma_f32_16x16x32_bf16 v[48:51], v[186:189], v[158:161], v[48:51]
	v_mfma_f32_16x16x32_bf16 v[44:47], v[190:193], v[158:161], v[44:47]
	v_mfma_f32_16x16x32_bf16 v[36:39], v[194:197], v[158:161], v[36:39]
	v_mfma_f32_16x16x32_bf16 v[32:35], v[182:185], v[158:161], v[32:35]
	s_waitcnt lgkmcnt(1)
	v_mfma_f32_16x16x32_bf16 v[28:31], v[186:189], v[162:165], v[28:31]
	v_mfma_f32_16x16x32_bf16 v[24:27], v[190:193], v[162:165], v[24:27]
	v_mfma_f32_16x16x32_bf16 v[20:23], v[194:197], v[162:165], v[20:23]
	v_mfma_f32_16x16x32_bf16 v[16:19], v[182:185], v[162:165], v[16:19]
	s_waitcnt lgkmcnt(0)
	v_mfma_f32_16x16x32_bf16 v[12:15], v[186:189], v[166:169], v[12:15]
	v_mfma_f32_16x16x32_bf16 v[8:11], v[190:193], v[166:169], v[8:11]
	v_mfma_f32_16x16x32_bf16 v[4:7], v[194:197], v[166:169], v[4:7]
	v_mfma_f32_16x16x32_bf16 v[0:3], v[182:185], v[166:169], v[0:3]
	s_mov_b64 vcc, s[14:15]
	s_cbranch_vccz .Ls5g_lo_a
	s_waitcnt vmcnt(15)
	ds_write_b128 v146, v[92:95] offset:32768
	s_waitcnt vmcnt(14)
	ds_write_b128 v146, v[100:103] offset:36864
	s_waitcnt vmcnt(13)
	ds_write_b128 v146, v[104:107] offset:40960
	s_waitcnt vmcnt(12)
	ds_write_b128 v146, v[112:115] offset:45056
	s_waitcnt vmcnt(11)
	ds_write_b128 v146, v[116:119] offset:49152
	s_waitcnt vmcnt(10)
	ds_write_b128 v146, v[120:123] offset:53248
	s_waitcnt vmcnt(9)
	ds_write_b128 v146, v[124:127] offset:57344
	s_waitcnt vmcnt(8)
	ds_write_b128 v146, v[128:131] offset:61440
	s_branch .Ls5g_done_a

; #define GLOAD(RA, RB, kt) { const int k_ = (kt) * 64 + lc * 8; const long ko_ = (long)(k_ >> a.segshift) * a.segstride + (k_ & segmask); \
;     _Pragma("unroll") for (int i = 0; i < 4; ++i) RA[i] = *(const u32x4*)(ap[i] + ko_); \
;     _Pragma("unroll") for (int i = 0; i < NBL; ++i) RB[i] = *(const u32x4*)(bp + (long)(32 * i) * ldb + (kt) * 64); }
; #define LSTORE(RA, RB, buf) { char* s_ = smem + (buf) * STAGE; \
;     _Pragma("unroll") for (int i = 0; i < 4; ++i) *(u32x4*)(s_ + wofs + i * 4096) = RA[i]; \
;     _Pragma("unroll") for (int i = 0; i < NBL; ++i) *(u32x4*)(s_ + ABYTES + wofs + i * 4096) = RB[i]; }
; #define BAR() { asm volatile("s_waitcnt lgkmcnt(0)" ::: "memory"); __builtin_amdgcn_s_barrier(); asm volatile("" ::: "memory"); }
; template <int WN, bool SWAP>
; DEV void gemm_core(f32x4 (&acc)[4][WN], const ASrc& a, const bf16_t* __restrict__ Bt, long ldb, int K, char* smem) {
;     ...
;   __builtin_amdgcn_sched_barrier(0);
;   GLOAD(ra0, rb0, 0); GLOAD(ra1, rb1, 1); LSTORE(ra0, rb0, 0); BAR();
; #pragma nounroll
;   for (int kt = 0; kt < nk; kt += 2) {
;     if (kt + 2 < nk) GLOAD(ra0, rb0, kt + 2);
;     COMPUTE(0);
;     LSTORE(ra1, rb1, 1);
;     BAR();
;     if (kt + 3 < nk) GLOAD(ra1, rb1, kt + 3);
;     COMPUTE(1);
.Ls5g_done_a:
	s_waitcnt lgkmcnt(0)
	s_barrier
	s_cmp_ge_i32 s24, s7
	s_cbranch_scc1 .LBB0_125
	v_add_u32_e32 v198, s12, v145
	v_lshrrev_b32_e32 v104, 4, v198
	v_mad_u64_u32 v[198:199], s[26:27], v104, s53, v[136:137]
	v_mad_u64_u32 v[100:101], s[26:27], v104, s53, v[138:139]
	global_load_dwordx4 v[92:95], v[198:199], off
	s_nop 0
	global_load_dwordx4 v[100:103], v[100:101], off
	v_mad_u64_u32 v[198:199], s[26:27], v104, s53, v[140:141]
	v_mad_u64_u32 v[112:113], s[26:27], v104, s53, v[142:143]
	s_mov_b32 s13, s85
	global_load_dwordx4 v[104:107], v[198:199], off
	s_nop 0
	global_load_dwordx4 v[112:115], v[112:113], off
	v_lshl_add_u64 v[198:199], s[12:13], 1, v[134:135]
	v_add_co_u32_e32 v120, vcc, 0x8000, v198
	s_nop 1
	v_addc_co_u32_e32 v121, vcc, 0, v199, vcc
	v_add_co_u32_e32 v124, vcc, 0x10000, v198
	global_load_dwordx4 v[116:119], v[198:199], off
	s_nop 0
	global_load_dwordx4 v[120:123], v[120:121], off
	v_addc_co_u32_e32 v125, vcc, 0, v199, vcc
	v_add_co_u32_e32 v198, vcc, 0x18000, v198
	s_nop 1
	v_addc_co_u32_e32 v199, vcc, 0, v199, vcc
	global_load_dwordx4 v[124:127], v[124:125], off
	s_nop 0
	global_load_dwordx4 v[128:131], v[198:199], off
.LBB0_125:
	v_add_u32_e32 v151, v147, v149
	v_add_u32_e32 v153, v148, v149
	v_add_u32_e32 v152, v147, v150
	v_add_u32_e32 v199, v148, v150
	ds_read_b128 v[170:173], v153 offset:49152
	ds_read_b128 v[174:177], v153 offset:51200
	ds_read_b128 v[178:181], v153 offset:53248
	ds_read_b128 v[182:185], v153 offset:55296
	ds_read_b128 v[154:157], v151 offset:32768
	ds_read_b128 v[158:161], v151 offset:34816
	ds_read_b128 v[162:165], v151 offset:36864
	ds_read_b128 v[166:169], v151 offset:38912
	s_waitcnt lgkmcnt(3)
	v_mfma_f32_16x16x32_bf16 v[64:67], v[170:173], v[154:157], v[64:67]
	v_mfma_f32_16x16x32_bf16 v[60:63], v[174:177], v[154:157], v[60:63]
	v_mfma_f32_16x16x32_bf16 v[56:59], v[178:181], v[154:157], v[56:59]
	v_mfma_f32_16x16x32_bf16 v[52:55], v[182:185], v[154:157], v[52:55]
	ds_read_b128 v[186:189], v199 offset:49152
	s_waitcnt lgkmcnt(3)
	v_mfma_f32_16x16x32_bf16 v[48:51], v[170:173], v[158:161], v[48:51]
	v_mfma_f32_16x16x32_bf16 v[44:47], v[174:177], v[158:161], v[44:47]
	v_mfma_f32_16x16x32_bf16 v[36:39], v[178:181], v[158:161], v[36:39]
	v_mfma_f32_16x16x32_bf16 v[32:35], v[182:185], v[158:161], v[32:35]
	ds_read_b128 v[190:193], v199 offset:51200
	s_waitcnt lgkmcnt(3)
	v_mfma_f32_16x16x32_bf16 v[28:31], v[170:173], v[162:165], v[28:31]
	v_mfma_f32_16x16x32_bf16 v[24:27], v[174:177], v[162:165], v[24:27]
	v_mfma_f32_16x16x32_bf16 v[20:23], v[178:181], v[162:165], v[20:23]
	v_mfma_f32_16x16x32_bf16 v[16:19], v[182:185], v[162:165], v[16:19]
	ds_read_b128 v[194:197], v199 offset:53248
	s_waitcnt lgkmcnt(3)
	v_mfma_f32_16x16x32_bf16 v[12:15], v[170:173], v[166:169], v[12:15]
	v_mfma_f32_16x16x32_bf16 v[8:11], v[174:177], v[166:169], v[8:11]
	v_mfma_f32_16x16x32_bf16 v[4:7], v[178:181], v[166:169], v[4:7]
	v_mfma_f32_16x16x32_bf16 v[0:3], v[182:185], v[166:169], v[0:3]
	ds_read_b128 v[182:185], v199 offset:55296
	ds_read_b128 v[154:157], v152 offset:32768
	ds_read_b128 v[158:161], v152 offset:34816
	ds_read_b128 v[162:165], v152 offset:36864
	ds_read_b128 v[166:169], v152 offset:38912
	s_waitcnt lgkmcnt(3)
	v_mfma_f32_16x16x32_bf16 v[64:67], v[186:189], v[154:157], v[64:67]
	v_mfma_f32_16x16x32_bf16 v[60:63], v[190:193], v[154:157], v[60:63]
	v_mfma_f32_16x16x32_bf16 v[56:59], v[194:197], v[154:157], v[56:59]
	v_mfma_f32_16x16x32_bf16 v[52:55], v[182:185], v[154:157], v[52:55]
	s_waitcnt lgkmcnt(2)
	v_mfma_f32_16x16x32_bf16 v[48:51], v[186:189], v[158:161], v[48:51]
	v_mfma_f32_16x16x32_bf16 v[44:47], v[190:193], v[158:161], v[44:47]
	v_mfma_f32_16x16x32_bf16 v[36:39], v[194:197], v[158:161], v[36:39]
	v_mfma_f32_16x16x32_bf16 v[32:35], v[182:185], v[158:161], v[32:35]
	s_waitcnt lgkmcnt(1)
	v_mfma_f32_16x16x32_bf16 v[28:31], v[186:189], v[162:165], v[28:31]
	v_mfma_f32_16x16x32_bf16 v[24:27], v[190:193], v[162:165], v[24:27]
	v_mfma_f32_16x16x32_bf16 v[20:23], v[194:197], v[162:165], v[20:23]
	v_mfma_f32_16x16x32_bf16 v[16:19], v[182:185], v[162:165], v[16:19]
	s_waitcnt lgkmcnt(0)
	v_mfma_f32_16x16x32_bf16 v[12:15], v[186:189], v[166:169], v[12:15]
	v_mfma_f32_16x16x32_bf16 v[8:11], v[190:193], v[166:169], v[8:11]
	v_mfma_f32_16x16x32_bf16 v[4:7], v[194:197], v[166:169], v[4:7]
	v_mfma_f32_16x16x32_bf16 v[0:3], v[182:185], v[166:169], v[0:3]
	s_andn2_b64 vcc, exec, s[14:15]
	s_cbranch_vccnz .LBB0_120
	s_cmp_ge_i32 s24, s7
	s_cbranch_scc1 .Ls5g_w0_a
	s_waitcnt vmcnt(8)
	s_branch .Ls5g_st_a

; #define GLOAD(RA, RB, kt) { const int k_ = (kt) * 64 + lc * 8; const long ko_ = (long)(k_ >> a.segshift) * a.segstride + (k_ & segmask); \
;     _Pragma("unroll") for (int i = 0; i < 4; ++i) RA[i] = *(const u32x4*)(ap[i] + ko_); \
;     _Pragma("unroll") for (int i = 0; i < NBL; ++i) RB[i] = *(const u32x4*)(bp + (long)(32 * i) * ldb + (kt) * 64); }
; #define LSTORE(RA, RB, buf) { char* s_ = smem + (buf) * STAGE; \
;     _Pragma("unroll") for (int i = 0; i < 4; ++i) *(u32x4*)(s_ + wofs + i * 4096) = RA[i]; \
;     _Pragma("unroll") for (int i = 0; i < NBL; ++i) *(u32x4*)(s_ + ABYTES + wofs + i * 4096) = RB[i]; }
; #define BAR() { asm volatile("s_waitcnt lgkmcnt(0)" ::: "memory"); __builtin_amdgcn_s_barrier(); asm volatile("" ::: "memory"); }
; template <int WN, bool SWAP>
; DEV void gemm_core(f32x4 (&acc)[4][WN], const ASrc& a, const bf16_t* __restrict__ Bt, long ldb, int K, char* smem) {
;     ...
;   __builtin_amdgcn_sched_barrier(0);
;   GLOAD(ra0, rb0, 0); GLOAD(ra1, rb1, 1); LSTORE(ra0, rb0, 0); BAR();
; #pragma nounroll
;   for (int kt = 0; kt < nk; kt += 2) {
;     if (kt + 2 < nk) GLOAD(ra0, rb0, kt + 2);
;     COMPUTE(0);
;     LSTORE(ra1, rb1, 1);
.LBB0_133:
	v_add_u32_e32 v151, v147, v149
	v_add_u32_e32 v153, v148, v149
	v_add_u32_e32 v152, v147, v150
	v_add_u32_e32 v199, v148, v150
	ds_read_b128 v[170:173], v153 offset:16384
	ds_read_b128 v[174:177], v153 offset:18432
	ds_read_b128 v[178:181], v153 offset:20480
	ds_read_b128 v[182:185], v153 offset:22528
	ds_read_b128 v[154:157], v151 offset:0
	ds_read_b128 v[158:161], v151 offset:2048
	ds_read_b128 v[162:165], v151 offset:4096
	ds_read_b128 v[166:169], v151 offset:6144
	s_waitcnt lgkmcnt(3)
	v_mfma_f32_16x16x32_bf16 v[64:67], v[170:173], v[154:157], v[64:67]
	v_mfma_f32_16x16x32_bf16 v[60:63], v[174:177], v[154:157], v[60:63]
	v_mfma_f32_16x16x32_bf16 v[56:59], v[178:181], v[154:157], v[56:59]
	v_mfma_f32_16x16x32_bf16 v[52:55], v[182:185], v[154:157], v[52:55]
	ds_read_b128 v[186:189], v199 offset:16384
	s_waitcnt lgkmcnt(3)
	v_mfma_f32_16x16x32_bf16 v[48:51], v[170:173], v[158:161], v[48:51]
	v_mfma_f32_16x16x32_bf16 v[44:47], v[174:177], v[158:161], v[44:47]
	v_mfma_f32_16x16x32_bf16 v[36:39], v[178:181], v[158:161], v[36:39]
	v_mfma_f32_16x16x32_bf16 v[32:35], v[182:185], v[158:161], v[32:35]
	ds_read_b128 v[190:193], v199 offset:18432
	s_waitcnt lgkmcnt(3)
	v_mfma_f32_16x16x32_bf16 v[28:31], v[170:173], v[162:165], v[28:31]
	v_mfma_f32_16x16x32_bf16 v[24:27], v[174:177], v[162:165], v[24:27]
	v_mfma_f32_16x16x32_bf16 v[20:23], v[178:181], v[162:165], v[20:23]
	v_mfma_f32_16x16x32_bf16 v[16:19], v[182:185], v[162:165], v[16:19]
	ds_read_b128 v[194:197], v199 offset:20480
	s_waitcnt lgkmcnt(3)
	v_mfma_f32_16x16x32_bf16 v[12:15], v[170:173], v[166:169], v[12:15]
	v_mfma_f32_16x16x32_bf16 v[8:11], v[174:177], v[166:169], v[8:11]
	v_mfma_f32_16x16x32_bf16 v[4:7], v[178:181], v[166:169], v[4:7]
	v_mfma_f32_16x16x32_bf16 v[0:3], v[182:185], v[166:169], v[0:3]
	ds_read_b128 v[182:185], v199 offset:22528
	ds_read_b128 v[154:157], v152 offset:0
	ds_read_b128 v[158:161], v152 offset:2048
	ds_read_b128 v[162:165], v152 offset:4096
	ds_read_b128 v[166:169], v152 offset:6144
	s_waitcnt lgkmcnt(3)
	v_mfma_f32_16x16x32_bf16 v[64:67], v[186:189], v[154:157], v[64:67]
	v_mfma_f32_16x16x32_bf16 v[60:63], v[190:193], v[154:157], v[60:63]
	v_mfma_f32_16x16x32_bf16 v[56:59], v[194:197], v[154:157], v[56:59]
	v_mfma_f32_16x16x32_bf16 v[52:55], v[182:185], v[154:157], v[52:55]
	s_waitcnt lgkmcnt(2)
	v_mfma_f32_16x16x32_bf16 v[48:51], v[186:189], v[158:161], v[48:51]
	v_mfma_f32_16x16x32_bf16 v[44:47], v[190:193], v[158:161], v[44:47]
	v_mfma_f32_16x16x32_bf16 v[36:39], v[194:197], v[158:161], v[36:39]
	v_mfma_f32_16x16x32_bf16 v[32:35], v[182:185], v[158:161], v[32:35]
	s_waitcnt lgkmcnt(1)
	v_mfma_f32_16x16x32_bf16 v[28:31], v[186:189], v[162:165], v[28:31]
	v_mfma_f32_16x16x32_bf16 v[24:27], v[190:193], v[162:165], v[24:27]
	v_mfma_f32_16x16x32_bf16 v[20:23], v[194:197], v[162:165], v[20:23]
	v_mfma_f32_16x16x32_bf16 v[16:19], v[182:185], v[162:165], v[16:19]
	s_waitcnt lgkmcnt(0)
	v_mfma_f32_16x16x32_bf16 v[12:15], v[186:189], v[166:169], v[12:15]
	v_mfma_f32_16x16x32_bf16 v[8:11], v[190:193], v[166:169], v[8:11]
	v_mfma_f32_16x16x32_bf16 v[4:7], v[194:197], v[166:169], v[4:7]
	v_mfma_f32_16x16x32_bf16 v[0:3], v[182:185], v[166:169], v[0:3]
	s_mov_b64 vcc, s[8:9]
	s_cbranch_vccz .Ls5g_lo_b
	s_waitcnt vmcnt(15)
	ds_write_b128 v146, v[92:95] offset:32768
	s_waitcnt vmcnt(14)
	ds_write_b128 v146, v[96:99] offset:36864
	s_waitcnt vmcnt(13)
	ds_write_b128 v146, v[100:103] offset:40960
	s_waitcnt vmcnt(12)
	ds_write_b128 v146, v[104:107] offset:45056
	s_waitcnt vmcnt(11)
	ds_write_b128 v146, v[116:119] offset:49152
	s_waitcnt vmcnt(10)
	ds_write_b128 v146, v[120:123] offset:53248
	s_waitcnt vmcnt(9)
	ds_write_b128 v146, v[124:127] offset:57344
	s_waitcnt vmcnt(8)
	ds_write_b128 v146, v[128:131] offset:61440
	s_branch .Ls5g_done_b

; #define GLOAD(RA, RB, kt) { const int k_ = (kt) * 64 + lc * 8; const long ko_ = (long)(k_ >> a.segshift) * a.segstride + (k_ & segmask); \
;     _Pragma("unroll") for (int i = 0; i < 4; ++i) RA[i] = *(const u32x4*)(ap[i] + ko_); \
;     _Pragma("unroll") for (int i = 0; i < NBL; ++i) RB[i] = *(const u32x4*)(bp + (long)(32 * i) * ldb + (kt) * 64); }
; #define LSTORE(RA, RB, buf) { char* s_ = smem + (buf) * STAGE; \
;     _Pragma("unroll") for (int i = 0; i < 4; ++i) *(u32x4*)(s_ + wofs + i * 4096) = RA[i]; \
;     _Pragma("unroll") for (int i = 0; i < NBL; ++i) *(u32x4*)(s_ + ABYTES + wofs + i * 4096) = RB[i]; }
; #define BAR() { asm volatile("s_waitcnt lgkmcnt(0)" ::: "memory"); __builtin_amdgcn_s_barrier(); asm volatile("" ::: "memory"); }
; template <int WN, bool SWAP>
; DEV void gemm_core(f32x4 (&acc)[4][WN], const ASrc& a, const bf16_t* __restrict__ Bt, long ldb, int K, char* smem) {
;     ...
;   __builtin_amdgcn_sched_barrier(0);
;   GLOAD(ra0, rb0, 0); GLOAD(ra1, rb1, 1); LSTORE(ra0, rb0, 0); BAR();
; #pragma nounroll
;   for (int kt = 0; kt < nk; kt += 2) {
;     if (kt + 2 < nk) GLOAD(ra0, rb0, kt + 2);
;     COMPUTE(0);
;     LSTORE(ra1, rb1, 1);
;     BAR();
;     if (kt + 3 < nk) GLOAD(ra1, rb1, kt + 3);
;     COMPUTE(1);
.Ls5g_done_b:
	s_waitcnt lgkmcnt(0)
	s_barrier
	s_cmp_ge_i32 s13, s12
	s_cbranch_scc1 .LBB0_135
	s_and_b32 s7, s6, 0x3fffffc0
	v_or_b32_e32 v40, s7, v145
	v_lshlrev_b32_e32 v40, 1, v40
	v_lshl_add_u64 v[198:199], v[134:135], 0, v[40:41]
	v_lshl_add_u64 v[96:97], v[136:137], 0, v[40:41]
	global_load_dwordx4 v[92:95], v[198:199], off
	s_nop 0
	global_load_dwordx4 v[96:99], v[96:97], off
	v_lshl_add_u64 v[198:199], v[138:139], 0, v[40:41]
	v_lshl_add_u64 v[104:105], v[140:141], 0, v[40:41]
	s_mov_b32 s7, s85
	global_load_dwordx4 v[100:103], v[198:199], off
	s_nop 0
	global_load_dwordx4 v[104:107], v[104:105], off
	v_lshl_add_u64 v[198:199], s[6:7], 1, v[142:143]
	v_add_co_u32_e32 v120, vcc, 0x4000, v198
	s_nop 1
	v_addc_co_u32_e32 v121, vcc, 0, v199, vcc
	v_add_co_u32_e32 v124, vcc, 0x8000, v198
	global_load_dwordx4 v[116:119], v[198:199], off
	s_nop 0
	global_load_dwordx4 v[120:123], v[120:121], off
	v_addc_co_u32_e32 v125, vcc, 0, v199, vcc
	v_add_co_u32_e32 v198, vcc, 0xc000, v198
	s_nop 1
	v_addc_co_u32_e32 v199, vcc, 0, v199, vcc
	global_load_dwordx4 v[124:127], v[124:125], off
	s_nop 0
	global_load_dwordx4 v[128:131], v[198:199], off
.LBB0_135:
	v_add_u32_e32 v151, v147, v149
	v_add_u32_e32 v153, v148, v149
	v_add_u32_e32 v152, v147, v150
	v_add_u32_e32 v199, v148, v150
	ds_read_b128 v[170:173], v153 offset:49152
	ds_read_b128 v[174:177], v153 offset:51200
	ds_read_b128 v[178:181], v153 offset:53248
	ds_read_b128 v[182:185], v153 offset:55296
	ds_read_b128 v[154:157], v151 offset:32768
	ds_read_b128 v[158:161], v151 offset:34816
	ds_read_b128 v[162:165], v151 offset:36864
	ds_read_b128 v[166:169], v151 offset:38912
	s_waitcnt lgkmcnt(3)
	v_mfma_f32_16x16x32_bf16 v[64:67], v[170:173], v[154:157], v[64:67]
	v_mfma_f32_16x16x32_bf16 v[60:63], v[174:177], v[154:157], v[60:63]
	v_mfma_f32_16x16x32_bf16 v[56:59], v[178:181], v[154:157], v[56:59]
	v_mfma_f32_16x16x32_bf16 v[52:55], v[182:185], v[154:157], v[52:55]
	ds_read_b128 v[186:189], v199 offset:49152
	s_waitcnt lgkmcnt(3)
	v_mfma_f32_16x16x32_bf16 v[48:51], v[170:173], v[158:161], v[48:51]
	v_mfma_f32_16x16x32_bf16 v[44:47], v[174:177], v[158:161], v[44:47]
	v_mfma_f32_16x16x32_bf16 v[36:39], v[178:181], v[158:161], v[36:39]
	v_mfma_f32_16x16x32_bf16 v[32:35], v[182:185], v[158:161], v[32:35]
	ds_read_b128 v[190:193], v199 offset:51200
	s_waitcnt lgkmcnt(3)
	v_mfma_f32_16x16x32_bf16 v[28:31], v[170:173], v[162:165], v[28:31]
	v_mfma_f32_16x16x32_bf16 v[24:27], v[174:177], v[162:165], v[24:27]
	v_mfma_f32_16x16x32_bf16 v[20:23], v[178:181], v[162:165], v[20:23]
	v_mfma_f32_16x16x32_bf16 v[16:19], v[182:185], v[162:165], v[16:19]
	ds_read_b128 v[194:197], v199 offset:53248
	s_waitcnt lgkmcnt(3)
	v_mfma_f32_16x16x32_bf16 v[12:15], v[170:173], v[166:169], v[12:15]
	v_mfma_f32_16x16x32_bf16 v[8:11], v[174:177], v[166:169], v[8:11]
	v_mfma_f32_16x16x32_bf16 v[4:7], v[178:181], v[166:169], v[4:7]
	v_mfma_f32_16x16x32_bf16 v[0:3], v[182:185], v[166:169], v[0:3]
	ds_read_b128 v[182:185], v199 offset:55296
	ds_read_b128 v[154:157], v152 offset:32768
	ds_read_b128 v[158:161], v152 offset:34816
	ds_read_b128 v[162:165], v152 offset:36864
	ds_read_b128 v[166:169], v152 offset:38912
	s_waitcnt lgkmcnt(3)
	v_mfma_f32_16x16x32_bf16 v[64:67], v[186:189], v[154:157], v[64:67]
	v_mfma_f32_16x16x32_bf16 v[60:63], v[190:193], v[154:157], v[60:63]
	v_mfma_f32_16x16x32_bf16 v[56:59], v[194:197], v[154:157], v[56:59]
	v_mfma_f32_16x16x32_bf16 v[52:55], v[182:185], v[154:157], v[52:55]
	s_waitcnt lgkmcnt(2)
	v_mfma_f32_16x16x32_bf16 v[48:51], v[186:189], v[158:161], v[48:51]
	v_mfma_f32_16x16x32_bf16 v[44:47], v[190:193], v[158:161], v[44:47]
	v_mfma_f32_16x16x32_bf16 v[36:39], v[194:197], v[158:161], v[36:39]
	v_mfma_f32_16x16x32_bf16 v[32:35], v[182:185], v[158:161], v[32:35]
	s_waitcnt lgkmcnt(1)
	v_mfma_f32_16x16x32_bf16 v[28:31], v[186:189], v[162:165], v[28:31]
	v_mfma_f32_16x16x32_bf16 v[24:27], v[190:193], v[162:165], v[24:27]
	v_mfma_f32_16x16x32_bf16 v[20:23], v[194:197], v[162:165], v[20:23]
	v_mfma_f32_16x16x32_bf16 v[16:19], v[182:185], v[162:165], v[16:19]
	s_waitcnt lgkmcnt(0)
	v_mfma_f32_16x16x32_bf16 v[12:15], v[186:189], v[166:169], v[12:15]
	v_mfma_f32_16x16x32_bf16 v[8:11], v[190:193], v[166:169], v[8:11]
	v_mfma_f32_16x16x32_bf16 v[4:7], v[194:197], v[166:169], v[4:7]
	v_mfma_f32_16x16x32_bf16 v[0:3], v[182:185], v[166:169], v[0:3]
	s_andn2_b64 vcc, exec, s[8:9]
	s_cbranch_vccnz .LBB0_130
	s_cmp_ge_i32 s13, s12
	s_cbranch_scc1 .Ls5g_w0_b
	s_waitcnt vmcnt(8)
	s_branch .Ls5g_st_b
